# last layer: P1 meta-row skinny GEMM covers only the mixer-input column groups (2 rounds instead of 3)
# baseline (speedup 1.0000x reference)
; #define MFMA16(a, b, c) __builtin_amdgcn_mfma_f32_16x16x32_bf16((a), (b), (c), 0, 0, 0)
;     __device__ __forceinline__ void apply(int row, int tile, int g, f32x4 v, f32x4) const { *(u32x2*)(O + (size_t)row * D + 16 * tile + 4 * g) = pack4(v); }
; template <class SE> __device__ __forceinline__ void skinny_gemm(const Frame& F, const bf16* Am, const bf16* Bt, int ntiles, int K, const SE& E) {
;     ...
;     for (int tile = F.bx; tile < ntiles; tile += F.G) {
;         const bf16* ap = Am + (size_t)j * K + 8 * g;
;         const bf16* b0 = Bt + (size_t)(E.brow(tile, 0) + j) * K + 8 * g;
;         const bf16* b1 = Bt + (size_t)(E.brow(tile, 1) + j) * K + 8 * g;
;         f32x4 acc0 = {0.f, 0.f, 0.f, 0.f}, acc1 = {0.f, 0.f, 0.f, 0.f};
; #pragma unroll 1
;         for (int s0 = sb; s0 < se; s0 += 8) {
;             const int n = (se - s0) < 8 ? (se - s0) : 8;
;             bf16x8 av[8], bv[8], cv[8];
; #pragma unroll
;             for (int q = 0; q < 8; ++q) if (q < n) { av[q] = *(const bf16x8*)(ap + 32 * (s0 + q)); bv[q] = *(const bf16x8*)(b0 + 32 * (s0 + q)); if (SE::DUAL) cv[q] = *(const bf16x8*)(b1 + 32 * (s0 + q)); }
; #pragma unroll
;             for (int q = 0; q < 8; ++q) if (q < n) { acc0 = MFMA16(bv[q], av[q], acc0); if (SE::DUAL) acc1 = MFMA16(cv[q], av[q], acc1); }
;         }
;         part[w * 64 + F.lane] = acc0; if (SE::DUAL) part[512 + w * 64 + F.lane] = acc1;
;         asm volatile("s_waitcnt lgkmcnt(0)" ::: "memory"); __builtin_amdgcn_s_barrier(); asm volatile("" ::: "memory");
;         if (w == 0) {
;             f32x4 t0 = part[F.lane], t1 = {0.f, 0.f, 0.f, 0.f}; if (SE::DUAL) t1 = part[512 + F.lane];
; #pragma unroll
;             for (int ww = 1; ww < 8; ++ww) { t0 += part[ww * 64 + F.lane]; if (SE::DUAL) t1 += part[512 + ww * 64 + F.lane]; }
;             E.apply(MF + j, tile, g, t0, t1);
;         }
;         asm volatile("s_waitcnt lgkmcnt(0)" ::: "memory"); __builtin_amdgcn_s_barrier(); asm volatile("" ::: "memory");
.LBB0_181:
	s_waitcnt lgkmcnt(0)
	s_barrier
	v_readlane_b32 s98, v255, 52
	s_cmp_eq_u32 s82, 0x100
	s_cselect_b32 s99, 0x80, 0
	s_movk_i32 vcc_lo, 0x300
	s_cselect_b32 vcc_lo, 0x280, vcc_lo
	s_andn2_b32 s99, s99, s98
	s_add_i32 s66, s66, s82
	s_add_i32 s66, s66, s99
	s_cmp_lg_u32 s98, 0
	s_cselect_b32 s98, 0x400, vcc_lo
	s_cmp_lt_i32 s66, s98
	s_cbranch_scc0 .LBB0_259
